# P4: gate-row loads hoisted (11 of 16) + staging loop issues its three loads together (vmcnt(2) instead of vmcnt(0) between them)
# speedup vs baseline: 1.0093x; 1.0093x over previous
.LBB0_482:
	v_readlane_b32 s0, v254, 28
	s_and_b32 s6, s15, 3
	s_and_b32 s7, s14, 0xffffff80
	v_mov_b32_e32 v0, s0
	ds_read_b64 v[2:3], v0
	v_mov_b32_e32 v0, v1
	v_readlane_b32 s0, v252, 8
	v_mbcnt_lo_u32_b32 v0, -1, v0
	v_mbcnt_hi_u32_b32 v146, -1, v0
	s_waitcnt lgkmcnt(0)
	v_readfirstlane_b32 s8, v3
	v_add_u32_e32 v108, s0, v146
	v_and_b32_e32 v0, 15, v146
	v_readfirstlane_b32 s2, v108
	s_and_b32 s10, s2, 0xffffffc0
	s_ashr_i32 s11, s10, 31
	s_add_u32 s0, s48, s10
	s_addc_u32 s1, s49, s11
	v_lshl_add_u64 v[106:107], s[0:1], 0, v[0:1]
	v_readfirstlane_b32 s9, v2
	v_bfe_u32 v147, v108, 4, 2
	v_lshlrev_b64 v[2:3], 9, v[106:107]
	v_lshl_add_u64 v[2:3], s[40:41], 0, v[2:3]
	s_waitcnt vmcnt(9)
	v_lshlrev_b32_e32 v4, 4, v147
	v_mov_b32_e32 v5, v1
	v_lshl_add_u64 v[98:99], v[2:3], 0, v[4:5]
	s_movk_i32 s0, 0x2000
	v_add_co_u32_e32 v100, vcc, s0, v98
	s_movk_i32 s0, 0x4000
	s_nop 0
	v_addc_co_u32_e32 v101, vcc, 0, v99, vcc
	v_add_co_u32_e32 v102, vcc, s0, v98
	s_movk_i32 s0, 0x6000
	s_nop 0
	v_addc_co_u32_e32 v103, vcc, 0, v99, vcc
	v_add_co_u32_e32 v104, vcc, s0, v98
	s_ashr_i32 s17, s2, 6
	s_lshl_b32 s0, s6, 22
	s_add_u32 s0, s38, s0
	s_addc_u32 s1, s39, 0
	s_lshl_b32 s16, s6, 9
	s_waitcnt vmcnt(7)
	v_ashrrev_i32_e32 v83, 5, v108
	v_and_b32_e32 v82, 31, v146
	s_add_u32 s4, s12, s16
	s_waitcnt vmcnt(5)
	v_add_u32_e32 v74, s7, v83
	s_addc_u32 s5, s13, 0
	v_lshlrev_b32_e32 v80, 4, v82
	v_mov_b32_e32 v81, v1
	v_ashrrev_i32_e32 v75, 31, v74
	v_lshl_add_u64 v[78:79], s[4:5], 0, v[80:81]
	v_lshlrev_b64 v[66:67], 9, v[74:75]
	v_lshlrev_b64 v[74:75], 11, v[74:75]
	v_addc_co_u32_e32 v105, vcc, 0, v99, vcc
	v_lshl_add_u64 v[74:75], v[78:79], 0, v[74:75]
	global_load_dwordx4 v[50:53], v[98:99], off nt
	global_load_dwordx4 v[54:57], v[100:101], off nt
	global_load_dwordx4 v[58:61], v[102:103], off nt
	global_load_dwordx4 v[62:65], v[104:105], off nt
	global_load_dwordx4 v[38:41], v[98:99], off offset:64 nt
	global_load_dwordx4 v[42:45], v[100:101], off offset:64 nt
	global_load_dwordx4 v[46:49], v[102:103], off offset:64 nt
	global_load_dwordx4 v[34:37], v[104:105], off offset:64 nt
	global_load_dwordx4 v[30:33], v[98:99], off offset:128 nt
	global_load_dwordx4 v[26:29], v[100:101], off offset:128 nt
	global_load_dwordx4 v[22:25], v[102:103], off offset:128 nt
	global_load_dwordx4 v[18:21], v[104:105], off offset:128 nt
	global_load_dwordx4 v[6:9], v[98:99], off offset:192 nt
	global_load_dwordx4 v[10:13], v[100:101], off offset:192 nt
	global_load_dwordx4 v[14:17], v[102:103], off offset:192 nt
	global_load_dwordx4 v[2:5], v[104:105], off offset:192 nt
	s_barrier
	global_load_dwordx4 v[74:77], v[74:75], off nt
	v_lshl_add_u64 v[66:67], s[0:1], 0, v[66:67]
	s_waitcnt vmcnt(21)
	v_lshl_add_u64 v[70:71], v[66:67], 0, v[80:81]
	s_mov_b32 s2, 0xa000000
	v_add_co_u32_e32 v66, vcc, s2, v70
	s_mov_b32 s4, 0x9000000
	s_nop 0
	v_addc_co_u32_e32 v67, vcc, 0, v71, vcc
	global_load_dwordx4 v[66:69], v[66:67], off nt
	v_add_co_u32_e32 v70, vcc, s4, v70
	s_add_i32 s18, 0, 0x10000
	s_nop 0
	v_addc_co_u32_e32 v71, vcc, 0, v71, vcc
	global_load_dwordx4 v[70:73], v[70:71], off nt
	v_lshl_or_b32 v111, s17, 4, v0
	v_or_b32_e32 v113, 4, v147
	v_or_b32_e32 v114, 8, v147
	v_or_b32_e32 v115, 12, v147
	v_or_b32_e32 v116, 16, v147
	v_or_b32_e32 v118, 20, v147
	v_or_b32_e32 v119, 24, v147
	v_or_b32_e32 v123, 28, v147
	v_lshlrev_b32_e32 v109, 9, v0
	v_add_u32_e32 v117, s18, v109
	v_lshlrev_b32_e32 v148, 2, v147
	v_mov_b32_e32 v112, 0
	s_cmp_lt_i32 s17, 0
	s_waitcnt vmcnt(2)
	v_cvt_f32_f16_e32 v89, v75
	v_cvt_f32_f16_sdwa v93, v75 dst_sel:DWORD dst_unused:UNUSED_PAD src0_sel:WORD_1
	v_cvt_f32_f16_e32 v75, v76
	v_cvt_f32_f16_e32 v84, v74
	v_cvt_f32_f16_sdwa v85, v74 dst_sel:DWORD dst_unused:UNUSED_PAD src0_sel:WORD_1
	v_cvt_f32_f16_e32 v91, v77
	v_cvt_f32_f16_sdwa v87, v76 dst_sel:DWORD dst_unused:UNUSED_PAD src0_sel:WORD_1
	v_mul_f32_e32 v76, 0x3fb8aa3b, v75
	v_mul_f32_e32 v75, 0xbfb8aa3b, v75
	v_cvt_f32_f16_sdwa v95, v77 dst_sel:DWORD dst_unused:UNUSED_PAD src0_sel:WORD_1
	v_mul_f32_e32 v77, 0xbfb8aa3b, v84
	v_exp_f32_e32 v86, v75
	v_mul_f32_e32 v75, 0x3fb8aa3b, v85
	v_mul_f32_e32 v85, 0xbfb8aa3b, v85
	v_mul_f32_e32 v88, 0x3fb8aa3b, v89
	v_mul_f32_e32 v89, 0xbfb8aa3b, v89
	v_mul_f32_e32 v74, 0x3fb8aa3b, v84
	v_exp_f32_e32 v84, v77
	v_exp_f32_e32 v85, v85
	v_exp_f32_e32 v92, v89
	v_mul_f32_e32 v89, 0xbfb8aa3b, v91
	v_exp_f32_e32 v94, v89
	v_mul_f32_e32 v89, 0x3fb8aa3b, v93
	v_mul_f32_e32 v93, 0xbfb8aa3b, v93
	v_exp_f32_e32 v93, v93
	v_mul_f32_e32 v77, 0x3fb8aa3b, v87
	v_mul_f32_e32 v87, 0xbfb8aa3b, v87
	s_waitcnt vmcnt(1)
	v_lshlrev_b32_e32 v96, 16, v66
	v_and_b32_e32 v97, 0xffff0000, v66
	v_exp_f32_e32 v87, v87
	v_pk_mul_f32 v[84:85], v[84:85], v[96:97]
	v_mul_f32_e32 v90, 0x3fb8aa3b, v91
	v_mul_f32_e32 v91, 0x3fb8aa3b, v95
	v_mul_f32_e32 v95, 0xbfb8aa3b, v95
	v_cvt_pk_bf16_f32 v66, v84, v85
	v_lshlrev_b32_e32 v84, 16, v67
	v_and_b32_e32 v85, 0xffff0000, v67
	v_exp_f32_e32 v95, v95
	v_pk_mul_f32 v[84:85], v[92:93], v[84:85]
	v_exp_f32_e32 v74, v74
	v_cvt_pk_bf16_f32 v67, v84, v85
	v_lshlrev_b32_e32 v84, 16, v68
	v_and_b32_e32 v85, 0xffff0000, v68
	v_pk_mul_f32 v[84:85], v[86:87], v[84:85]
	v_exp_f32_e32 v75, v75
	v_cvt_pk_bf16_f32 v68, v84, v85
	v_lshlrev_b32_e32 v84, 16, v69
	v_and_b32_e32 v85, 0xffff0000, v69
	v_pk_mul_f32 v[84:85], v[94:95], v[84:85]
	v_exp_f32_e32 v88, v88
	v_cvt_pk_bf16_f32 v69, v84, v85
	v_lshlrev_b32_e32 v85, 2, v83
	v_lshlrev_b32_e32 v84, 9, v83
	v_and_b32_e32 v85, 12, v85
	v_bfe_u32 v83, v83, 2, 2
	v_exp_f32_e32 v89, v89
	v_bitop3_b32 v83, v85, v82, v83 bitop3:0x36
	v_lshl_or_b32 v83, v83, 4, v84
	v_exp_f32_e32 v76, v76
	v_exp_f32_e32 v77, v77
	v_exp_f32_e32 v90, v90
	v_exp_f32_e32 v91, v91
	v_add_u32_e32 v84, s18, v83
	ds_write_b128 v84, v[66:69]
	s_waitcnt vmcnt(0)
	v_lshlrev_b32_e32 v66, 16, v70
	v_and_b32_e32 v67, 0xffff0000, v70
	v_lshlrev_b32_e32 v68, 16, v71
	v_and_b32_e32 v69, 0xffff0000, v71
	v_pk_mul_f32 v[66:67], v[74:75], v[66:67]
	v_pk_mul_f32 v[68:69], v[88:89], v[68:69]
	v_cvt_pk_bf16_f32 v66, v66, v67
	v_cvt_pk_bf16_f32 v67, v68, v69
	v_lshlrev_b32_e32 v68, 16, v72
	v_and_b32_e32 v69, 0xffff0000, v72
	v_lshlrev_b32_e32 v70, 16, v73
	v_and_b32_e32 v71, 0xffff0000, v73
	v_pk_mul_f32 v[68:69], v[76:77], v[68:69]
	v_pk_mul_f32 v[70:71], v[90:91], v[70:71]
	v_cvt_pk_bf16_f32 v68, v68, v69
	v_cvt_pk_bf16_f32 v69, v70, v71
	v_add_u32_e32 v70, 0, v83
	ds_write_b128 v70, v[66:69]
	v_add_u32_e32 v66, 0x200, v108
	v_ashrrev_i32_e32 v83, 5, v66
	v_add_u32_e32 v74, s7, v83
	v_ashrrev_i32_e32 v75, 31, v74
	v_lshlrev_b64 v[66:67], 9, v[74:75]
	v_lshl_add_u64 v[66:67], s[0:1], 0, v[66:67]
	v_lshl_add_u64 v[66:67], v[66:67], 0, v[80:81]
	v_add_co_u32_e32 v68, vcc, s2, v66
	v_lshlrev_b64 v[74:75], 11, v[74:75]
	s_nop 0
	v_addc_co_u32_e32 v69, vcc, 0, v67, vcc
	v_add_co_u32_e32 v66, vcc, s4, v66
	v_lshl_add_u64 v[74:75], v[78:79], 0, v[74:75]
	s_nop 0
	v_addc_co_u32_e32 v67, vcc, 0, v67, vcc
	global_load_dwordx4 v[70:73], v[68:69], off nt
	global_load_dwordx4 v[66:69], v[66:67], off nt
	global_load_dwordx4 v[74:77], v[74:75], off nt
	s_waitcnt vmcnt(2)
	v_lshlrev_b32_e32 v96, 16, v70
	v_and_b32_e32 v97, 0xffff0000, v70
	s_waitcnt vmcnt(0)
	v_cvt_f32_f16_e32 v89, v75
	v_cvt_f32_f16_sdwa v93, v75 dst_sel:DWORD dst_unused:UNUSED_PAD src0_sel:WORD_1
	v_cvt_f32_f16_e32 v75, v76
	v_cvt_f32_f16_e32 v84, v74
	v_cvt_f32_f16_sdwa v85, v74 dst_sel:DWORD dst_unused:UNUSED_PAD src0_sel:WORD_1
	v_cvt_f32_f16_e32 v91, v77
	v_cvt_f32_f16_sdwa v87, v76 dst_sel:DWORD dst_unused:UNUSED_PAD src0_sel:WORD_1
	v_mul_f32_e32 v76, 0x3fb8aa3b, v75
	v_mul_f32_e32 v75, 0xbfb8aa3b, v75
	v_cvt_f32_f16_sdwa v95, v77 dst_sel:DWORD dst_unused:UNUSED_PAD src0_sel:WORD_1
	v_mul_f32_e32 v77, 0xbfb8aa3b, v84
	v_exp_f32_e32 v86, v75
	v_mul_f32_e32 v75, 0x3fb8aa3b, v85
	v_mul_f32_e32 v85, 0xbfb8aa3b, v85
	v_mul_f32_e32 v88, 0x3fb8aa3b, v89
	v_mul_f32_e32 v89, 0xbfb8aa3b, v89
	v_mul_f32_e32 v74, 0x3fb8aa3b, v84
	v_exp_f32_e32 v84, v77
	v_exp_f32_e32 v85, v85
	v_exp_f32_e32 v92, v89
	v_mul_f32_e32 v89, 0xbfb8aa3b, v91
	v_exp_f32_e32 v94, v89
	v_mul_f32_e32 v89, 0x3fb8aa3b, v93
	v_mul_f32_e32 v93, 0xbfb8aa3b, v93
	v_exp_f32_e32 v93, v93
	v_mul_f32_e32 v77, 0x3fb8aa3b, v87
	v_mul_f32_e32 v87, 0xbfb8aa3b, v87
	v_exp_f32_e32 v87, v87
	v_pk_mul_f32 v[84:85], v[84:85], v[96:97]
	v_mul_f32_e32 v90, 0x3fb8aa3b, v91
	v_mul_f32_e32 v91, 0x3fb8aa3b, v95
	v_mul_f32_e32 v95, 0xbfb8aa3b, v95
	v_cvt_pk_bf16_f32 v70, v84, v85
	v_lshlrev_b32_e32 v84, 16, v71
	v_and_b32_e32 v85, 0xffff0000, v71
	v_exp_f32_e32 v95, v95
	v_pk_mul_f32 v[84:85], v[92:93], v[84:85]
	v_exp_f32_e32 v74, v74
	v_cvt_pk_bf16_f32 v71, v84, v85
	v_lshlrev_b32_e32 v84, 16, v72
	v_and_b32_e32 v85, 0xffff0000, v72
	v_pk_mul_f32 v[84:85], v[86:87], v[84:85]
	v_exp_f32_e32 v75, v75
	v_cvt_pk_bf16_f32 v72, v84, v85
	v_lshlrev_b32_e32 v84, 16, v73
	v_and_b32_e32 v85, 0xffff0000, v73
	v_pk_mul_f32 v[84:85], v[94:95], v[84:85]
	v_exp_f32_e32 v88, v88
	v_cvt_pk_bf16_f32 v73, v84, v85
	v_lshlrev_b32_e32 v85, 2, v83
	v_lshlrev_b32_e32 v84, 9, v83
	v_and_b32_e32 v85, 12, v85
	v_bfe_u32 v83, v83, 2, 2
	v_bitop3_b32 v83, v85, v82, v83 bitop3:0x36
	v_lshl_or_b32 v83, v83, 4, v84
	v_exp_f32_e32 v89, v89
	v_add_u32_e32 v84, s18, v83
	ds_write_b128 v84, v[70:73]
	v_lshlrev_b32_e32 v70, 16, v66
	v_and_b32_e32 v71, 0xffff0000, v66
	v_exp_f32_e32 v76, v76
	v_exp_f32_e32 v77, v77
	v_pk_mul_f32 v[70:71], v[74:75], v[70:71]
	v_exp_f32_e32 v90, v90
	v_cvt_pk_bf16_f32 v66, v70, v71
	v_lshlrev_b32_e32 v70, 16, v67
	v_and_b32_e32 v71, 0xffff0000, v67
	v_exp_f32_e32 v91, v91
	v_pk_mul_f32 v[70:71], v[88:89], v[70:71]
	s_nop 0
	v_cvt_pk_bf16_f32 v67, v70, v71
	v_lshlrev_b32_e32 v70, 16, v68
	v_and_b32_e32 v71, 0xffff0000, v68
	v_pk_mul_f32 v[70:71], v[76:77], v[70:71]
	s_nop 0
	v_cvt_pk_bf16_f32 v68, v70, v71
	v_lshlrev_b32_e32 v70, 16, v69
	v_and_b32_e32 v71, 0xffff0000, v69
	v_pk_mul_f32 v[70:71], v[90:91], v[70:71]
	s_nop 0
	v_cvt_pk_bf16_f32 v69, v70, v71
	v_add_u32_e32 v70, 0, v83
	ds_write_b128 v70, v[66:69]
	v_add_u32_e32 v66, 0x400, v108
	v_ashrrev_i32_e32 v83, 5, v66
	v_add_u32_e32 v74, s7, v83
	v_ashrrev_i32_e32 v75, 31, v74
	v_lshlrev_b64 v[66:67], 9, v[74:75]
	v_lshlrev_b64 v[74:75], 11, v[74:75]
	v_lshl_add_u64 v[74:75], v[78:79], 0, v[74:75]
	global_load_dwordx4 v[74:77], v[74:75], off nt
	v_lshl_add_u64 v[66:67], s[0:1], 0, v[66:67]
	v_lshl_add_u64 v[70:71], v[66:67], 0, v[80:81]
	v_add_co_u32_e32 v66, vcc, s2, v70
	v_addc_co_u32_e32 v67, vcc, 0, v71, vcc
	global_load_dwordx4 v[66:69], v[66:67], off nt
	v_add_co_u32_e32 v70, vcc, s4, v70
	s_nop 0
	v_addc_co_u32_e32 v71, vcc, 0, v71, vcc
	global_load_dwordx4 v[70:73], v[70:71], off nt
	s_waitcnt vmcnt(2)
	v_cvt_f32_f16_e32 v89, v75
	v_cvt_f32_f16_sdwa v93, v75 dst_sel:DWORD dst_unused:UNUSED_PAD src0_sel:WORD_1
	v_cvt_f32_f16_e32 v75, v76
	v_cvt_f32_f16_e32 v84, v74
	v_cvt_f32_f16_sdwa v85, v74 dst_sel:DWORD dst_unused:UNUSED_PAD src0_sel:WORD_1
	v_cvt_f32_f16_e32 v91, v77
	v_cvt_f32_f16_sdwa v87, v76 dst_sel:DWORD dst_unused:UNUSED_PAD src0_sel:WORD_1
	v_mul_f32_e32 v76, 0x3fb8aa3b, v75
	v_mul_f32_e32 v75, 0xbfb8aa3b, v75
	v_cvt_f32_f16_sdwa v95, v77 dst_sel:DWORD dst_unused:UNUSED_PAD src0_sel:WORD_1
	v_mul_f32_e32 v77, 0xbfb8aa3b, v84
	v_exp_f32_e32 v86, v75
	v_mul_f32_e32 v75, 0x3fb8aa3b, v85
	v_mul_f32_e32 v85, 0xbfb8aa3b, v85
	v_mul_f32_e32 v88, 0x3fb8aa3b, v89
	v_mul_f32_e32 v89, 0xbfb8aa3b, v89
	v_mul_f32_e32 v74, 0x3fb8aa3b, v84
	v_exp_f32_e32 v84, v77
	v_exp_f32_e32 v85, v85
	v_exp_f32_e32 v92, v89
	v_mul_f32_e32 v89, 0xbfb8aa3b, v91
	v_exp_f32_e32 v94, v89
	v_mul_f32_e32 v89, 0x3fb8aa3b, v93
	v_mul_f32_e32 v93, 0xbfb8aa3b, v93
	v_exp_f32_e32 v93, v93
	v_mul_f32_e32 v77, 0x3fb8aa3b, v87
	v_mul_f32_e32 v87, 0xbfb8aa3b, v87
	v_exp_f32_e32 v87, v87
	v_mul_f32_e32 v90, 0x3fb8aa3b, v91
	v_mul_f32_e32 v91, 0x3fb8aa3b, v95
	v_mul_f32_e32 v95, 0xbfb8aa3b, v95
	v_exp_f32_e32 v95, v95
	v_exp_f32_e32 v74, v74
	v_exp_f32_e32 v75, v75
	v_exp_f32_e32 v88, v88
	v_exp_f32_e32 v89, v89
	v_exp_f32_e32 v76, v76
	v_exp_f32_e32 v77, v77
	v_exp_f32_e32 v90, v90
	v_exp_f32_e32 v91, v91
	s_waitcnt vmcnt(1)
	v_lshlrev_b32_e32 v96, 16, v66
	v_and_b32_e32 v97, 0xffff0000, v66
	v_pk_mul_f32 v[84:85], v[84:85], v[96:97]
	s_nop 0
	v_cvt_pk_bf16_f32 v66, v84, v85
	v_lshlrev_b32_e32 v84, 16, v67
	v_and_b32_e32 v85, 0xffff0000, v67
	v_pk_mul_f32 v[84:85], v[92:93], v[84:85]
	s_nop 0
	v_cvt_pk_bf16_f32 v67, v84, v85
	v_lshlrev_b32_e32 v84, 16, v68
	v_and_b32_e32 v85, 0xffff0000, v68
	v_pk_mul_f32 v[84:85], v[86:87], v[84:85]
	s_nop 0
	v_cvt_pk_bf16_f32 v68, v84, v85
	v_lshlrev_b32_e32 v84, 16, v69
	v_and_b32_e32 v85, 0xffff0000, v69
	v_pk_mul_f32 v[84:85], v[94:95], v[84:85]
	s_nop 0
	v_cvt_pk_bf16_f32 v69, v84, v85
	v_lshlrev_b32_e32 v85, 2, v83
	v_lshlrev_b32_e32 v84, 9, v83
	v_and_b32_e32 v85, 12, v85
	v_bfe_u32 v83, v83, 2, 2
	v_bitop3_b32 v83, v85, v82, v83 bitop3:0x36
	v_lshl_or_b32 v83, v83, 4, v84
	v_add_u32_e32 v84, s18, v83
	ds_write_b128 v84, v[66:69]
	s_waitcnt vmcnt(0)
	v_lshlrev_b32_e32 v66, 16, v70
	v_and_b32_e32 v67, 0xffff0000, v70
	v_lshlrev_b32_e32 v68, 16, v71
	v_and_b32_e32 v69, 0xffff0000, v71
	v_pk_mul_f32 v[66:67], v[74:75], v[66:67]
	v_pk_mul_f32 v[68:69], v[88:89], v[68:69]
	v_cvt_pk_bf16_f32 v66, v66, v67
	v_cvt_pk_bf16_f32 v67, v68, v69
	v_lshlrev_b32_e32 v68, 16, v72
	v_and_b32_e32 v69, 0xffff0000, v72
	v_lshlrev_b32_e32 v70, 16, v73
	v_and_b32_e32 v71, 0xffff0000, v73
	v_pk_mul_f32 v[68:69], v[76:77], v[68:69]
	v_pk_mul_f32 v[70:71], v[90:91], v[70:71]
	v_cvt_pk_bf16_f32 v68, v68, v69
	v_cvt_pk_bf16_f32 v69, v70, v71
	v_add_u32_e32 v70, 0, v83
	ds_write_b128 v70, v[66:69]
	v_add_u32_e32 v66, 0x600, v108
	v_ashrrev_i32_e32 v83, 5, v66
	v_add_u32_e32 v74, s7, v83
	v_ashrrev_i32_e32 v75, 31, v74
	v_lshlrev_b64 v[66:67], 9, v[74:75]
	v_lshl_add_u64 v[66:67], s[0:1], 0, v[66:67]
	v_lshl_add_u64 v[66:67], v[66:67], 0, v[80:81]
	v_add_co_u32_e32 v68, vcc, s2, v66
	v_lshlrev_b64 v[74:75], 11, v[74:75]
	s_nop 0
	v_addc_co_u32_e32 v69, vcc, 0, v67, vcc
	v_add_co_u32_e32 v66, vcc, s4, v66
	v_lshl_add_u64 v[74:75], v[78:79], 0, v[74:75]
	s_nop 0
	v_addc_co_u32_e32 v67, vcc, 0, v67, vcc
	global_load_dwordx4 v[70:73], v[68:69], off nt
	global_load_dwordx4 v[66:69], v[66:67], off nt
	global_load_dwordx4 v[74:77], v[74:75], off nt
	s_waitcnt vmcnt(2)
	v_lshlrev_b32_e32 v96, 16, v70
	v_and_b32_e32 v97, 0xffff0000, v70
	s_waitcnt vmcnt(0)
	v_cvt_f32_f16_e32 v89, v75
	v_cvt_f32_f16_sdwa v93, v75 dst_sel:DWORD dst_unused:UNUSED_PAD src0_sel:WORD_1
	v_cvt_f32_f16_e32 v75, v76
	v_cvt_f32_f16_e32 v84, v74
	v_cvt_f32_f16_sdwa v85, v74 dst_sel:DWORD dst_unused:UNUSED_PAD src0_sel:WORD_1
	v_cvt_f32_f16_e32 v91, v77
	v_cvt_f32_f16_sdwa v87, v76 dst_sel:DWORD dst_unused:UNUSED_PAD src0_sel:WORD_1
	v_mul_f32_e32 v76, 0x3fb8aa3b, v75
	v_mul_f32_e32 v75, 0xbfb8aa3b, v75
	v_cvt_f32_f16_sdwa v95, v77 dst_sel:DWORD dst_unused:UNUSED_PAD src0_sel:WORD_1
	v_mul_f32_e32 v77, 0xbfb8aa3b, v84
	v_exp_f32_e32 v86, v75
	v_mul_f32_e32 v75, 0x3fb8aa3b, v85
	v_mul_f32_e32 v85, 0xbfb8aa3b, v85
	v_mul_f32_e32 v88, 0x3fb8aa3b, v89
	v_mul_f32_e32 v89, 0xbfb8aa3b, v89
	v_mul_f32_e32 v74, 0x3fb8aa3b, v84
	v_exp_f32_e32 v84, v77
	v_exp_f32_e32 v85, v85
	v_exp_f32_e32 v92, v89
	v_mul_f32_e32 v89, 0xbfb8aa3b, v91
	v_exp_f32_e32 v94, v89
	v_mul_f32_e32 v89, 0x3fb8aa3b, v93
	v_mul_f32_e32 v93, 0xbfb8aa3b, v93
	v_exp_f32_e32 v93, v93
	v_mul_f32_e32 v77, 0x3fb8aa3b, v87
	v_mul_f32_e32 v87, 0xbfb8aa3b, v87
	v_exp_f32_e32 v87, v87
	v_pk_mul_f32 v[84:85], v[84:85], v[96:97]
	v_mul_f32_e32 v90, 0x3fb8aa3b, v91
	v_mul_f32_e32 v91, 0x3fb8aa3b, v95
	v_mul_f32_e32 v95, 0xbfb8aa3b, v95
	v_cvt_pk_bf16_f32 v70, v84, v85
	v_lshlrev_b32_e32 v84, 16, v71
	v_and_b32_e32 v85, 0xffff0000, v71
	v_exp_f32_e32 v95, v95
	v_pk_mul_f32 v[84:85], v[92:93], v[84:85]
	v_exp_f32_e32 v74, v74
	v_cvt_pk_bf16_f32 v71, v84, v85
	v_lshlrev_b32_e32 v84, 16, v72
	v_and_b32_e32 v85, 0xffff0000, v72
	v_pk_mul_f32 v[84:85], v[86:87], v[84:85]
	v_exp_f32_e32 v75, v75
	v_cvt_pk_bf16_f32 v72, v84, v85
	v_lshlrev_b32_e32 v84, 16, v73
	v_and_b32_e32 v85, 0xffff0000, v73
	v_pk_mul_f32 v[84:85], v[94:95], v[84:85]
	v_exp_f32_e32 v88, v88
	v_cvt_pk_bf16_f32 v73, v84, v85
	v_lshlrev_b32_e32 v85, 2, v83
	v_lshlrev_b32_e32 v84, 9, v83
	v_and_b32_e32 v85, 12, v85
	v_bfe_u32 v83, v83, 2, 2
	v_bitop3_b32 v83, v85, v82, v83 bitop3:0x36
	v_lshl_or_b32 v83, v83, 4, v84
	v_exp_f32_e32 v89, v89
	v_add_u32_e32 v84, s18, v83
	ds_write_b128 v84, v[70:73]
	v_lshlrev_b32_e32 v70, 16, v66
	v_and_b32_e32 v71, 0xffff0000, v66
	v_exp_f32_e32 v76, v76
	v_exp_f32_e32 v77, v77
	v_pk_mul_f32 v[70:71], v[74:75], v[70:71]
	v_exp_f32_e32 v90, v90
	v_cvt_pk_bf16_f32 v66, v70, v71
	v_lshlrev_b32_e32 v70, 16, v67
	v_and_b32_e32 v71, 0xffff0000, v67
	v_exp_f32_e32 v91, v91
	v_pk_mul_f32 v[70:71], v[88:89], v[70:71]
	s_nop 0
	v_cvt_pk_bf16_f32 v67, v70, v71
	v_lshlrev_b32_e32 v70, 16, v68
	v_and_b32_e32 v71, 0xffff0000, v68
	v_pk_mul_f32 v[70:71], v[76:77], v[70:71]
	s_nop 0
	v_cvt_pk_bf16_f32 v68, v70, v71
	v_lshlrev_b32_e32 v70, 16, v69
	v_and_b32_e32 v71, 0xffff0000, v69
	v_pk_mul_f32 v[70:71], v[90:91], v[70:71]
	s_nop 0
	v_cvt_pk_bf16_f32 v69, v70, v71
	v_add_u32_e32 v70, 0, v83
	ds_write_b128 v70, v[66:69]
	v_add_u32_e32 v66, 0x800, v108
	v_ashrrev_i32_e32 v83, 5, v66
	v_add_u32_e32 v74, s7, v83
	v_ashrrev_i32_e32 v75, 31, v74
	v_lshlrev_b64 v[66:67], 9, v[74:75]
	v_lshlrev_b64 v[74:75], 11, v[74:75]
	v_lshl_add_u64 v[74:75], v[78:79], 0, v[74:75]
	global_load_dwordx4 v[74:77], v[74:75], off nt
	v_lshl_add_u64 v[66:67], s[0:1], 0, v[66:67]
	v_lshl_add_u64 v[70:71], v[66:67], 0, v[80:81]
	v_add_co_u32_e32 v66, vcc, s2, v70
	v_addc_co_u32_e32 v67, vcc, 0, v71, vcc
	global_load_dwordx4 v[66:69], v[66:67], off nt
	v_add_co_u32_e32 v70, vcc, s4, v70
	s_nop 0
	v_addc_co_u32_e32 v71, vcc, 0, v71, vcc
	global_load_dwordx4 v[70:73], v[70:71], off nt
	s_waitcnt vmcnt(2)
	v_cvt_f32_f16_e32 v89, v75
	v_cvt_f32_f16_sdwa v93, v75 dst_sel:DWORD dst_unused:UNUSED_PAD src0_sel:WORD_1
	v_cvt_f32_f16_e32 v75, v76
	v_cvt_f32_f16_e32 v84, v74
	v_cvt_f32_f16_sdwa v85, v74 dst_sel:DWORD dst_unused:UNUSED_PAD src0_sel:WORD_1
	v_cvt_f32_f16_e32 v91, v77
	v_cvt_f32_f16_sdwa v87, v76 dst_sel:DWORD dst_unused:UNUSED_PAD src0_sel:WORD_1
	v_mul_f32_e32 v76, 0x3fb8aa3b, v75
	v_mul_f32_e32 v75, 0xbfb8aa3b, v75
	v_cvt_f32_f16_sdwa v95, v77 dst_sel:DWORD dst_unused:UNUSED_PAD src0_sel:WORD_1
	v_mul_f32_e32 v77, 0xbfb8aa3b, v84
	v_exp_f32_e32 v86, v75
	v_mul_f32_e32 v75, 0x3fb8aa3b, v85
	v_mul_f32_e32 v85, 0xbfb8aa3b, v85
	v_mul_f32_e32 v88, 0x3fb8aa3b, v89
	v_mul_f32_e32 v89, 0xbfb8aa3b, v89
	v_mul_f32_e32 v74, 0x3fb8aa3b, v84
	v_exp_f32_e32 v84, v77
	v_exp_f32_e32 v85, v85
	v_exp_f32_e32 v92, v89
	v_mul_f32_e32 v89, 0xbfb8aa3b, v91
	v_exp_f32_e32 v94, v89
	v_mul_f32_e32 v89, 0x3fb8aa3b, v93
	v_mul_f32_e32 v93, 0xbfb8aa3b, v93
	v_exp_f32_e32 v93, v93
	v_mul_f32_e32 v77, 0x3fb8aa3b, v87
	v_mul_f32_e32 v87, 0xbfb8aa3b, v87
	v_exp_f32_e32 v87, v87
	v_mul_f32_e32 v90, 0x3fb8aa3b, v91
	v_mul_f32_e32 v91, 0x3fb8aa3b, v95
	v_mul_f32_e32 v95, 0xbfb8aa3b, v95
	v_exp_f32_e32 v95, v95
	v_exp_f32_e32 v74, v74
	v_exp_f32_e32 v75, v75
	v_exp_f32_e32 v88, v88
	v_exp_f32_e32 v89, v89
	v_exp_f32_e32 v76, v76
	v_exp_f32_e32 v77, v77
	v_exp_f32_e32 v90, v90
	v_exp_f32_e32 v91, v91
	s_waitcnt vmcnt(1)
	v_lshlrev_b32_e32 v96, 16, v66
	v_and_b32_e32 v97, 0xffff0000, v66
	v_pk_mul_f32 v[84:85], v[84:85], v[96:97]
	s_nop 0
	v_cvt_pk_bf16_f32 v66, v84, v85
	v_lshlrev_b32_e32 v84, 16, v67
	v_and_b32_e32 v85, 0xffff0000, v67
	v_pk_mul_f32 v[84:85], v[92:93], v[84:85]
	s_nop 0
	v_cvt_pk_bf16_f32 v67, v84, v85
	v_lshlrev_b32_e32 v84, 16, v68
	v_and_b32_e32 v85, 0xffff0000, v68
	v_pk_mul_f32 v[84:85], v[86:87], v[84:85]
	s_nop 0
	v_cvt_pk_bf16_f32 v68, v84, v85
	v_lshlrev_b32_e32 v84, 16, v69
	v_and_b32_e32 v85, 0xffff0000, v69
	v_pk_mul_f32 v[84:85], v[94:95], v[84:85]
	s_nop 0
	v_cvt_pk_bf16_f32 v69, v84, v85
	v_lshlrev_b32_e32 v85, 2, v83
	v_lshlrev_b32_e32 v84, 9, v83
	v_and_b32_e32 v85, 12, v85
	v_bfe_u32 v83, v83, 2, 2
	v_bitop3_b32 v83, v85, v82, v83 bitop3:0x36
	v_lshl_or_b32 v83, v83, 4, v84
	v_add_u32_e32 v84, s18, v83
	ds_write_b128 v84, v[66:69]
	s_waitcnt vmcnt(0)
	v_lshlrev_b32_e32 v66, 16, v70
	v_and_b32_e32 v67, 0xffff0000, v70
	v_lshlrev_b32_e32 v68, 16, v71
	v_and_b32_e32 v69, 0xffff0000, v71
	v_pk_mul_f32 v[66:67], v[74:75], v[66:67]
	v_pk_mul_f32 v[68:69], v[88:89], v[68:69]
	v_cvt_pk_bf16_f32 v66, v66, v67
	v_cvt_pk_bf16_f32 v67, v68, v69
	v_lshlrev_b32_e32 v68, 16, v72
	v_and_b32_e32 v69, 0xffff0000, v72
	v_lshlrev_b32_e32 v70, 16, v73
	v_and_b32_e32 v71, 0xffff0000, v73
	v_pk_mul_f32 v[68:69], v[76:77], v[68:69]
	v_pk_mul_f32 v[70:71], v[90:91], v[70:71]
	v_cvt_pk_bf16_f32 v68, v68, v69
	v_cvt_pk_bf16_f32 v69, v70, v71
	v_add_u32_e32 v70, 0, v83
	ds_write_b128 v70, v[66:69]
	v_add_u32_e32 v66, 0xa00, v108
	v_ashrrev_i32_e32 v83, 5, v66
	v_add_u32_e32 v74, s7, v83
	v_ashrrev_i32_e32 v75, 31, v74
	v_lshlrev_b64 v[66:67], 9, v[74:75]
	v_lshl_add_u64 v[66:67], s[0:1], 0, v[66:67]
	v_lshl_add_u64 v[66:67], v[66:67], 0, v[80:81]
	v_add_co_u32_e32 v68, vcc, s2, v66
	v_lshlrev_b64 v[74:75], 11, v[74:75]
	s_nop 0
	v_addc_co_u32_e32 v69, vcc, 0, v67, vcc
	v_add_co_u32_e32 v66, vcc, s4, v66
	v_lshl_add_u64 v[74:75], v[78:79], 0, v[74:75]
	s_nop 0
	v_addc_co_u32_e32 v67, vcc, 0, v67, vcc
	global_load_dwordx4 v[70:73], v[68:69], off nt
	global_load_dwordx4 v[66:69], v[66:67], off nt
	global_load_dwordx4 v[74:77], v[74:75], off nt
	s_waitcnt vmcnt(2)
	v_lshlrev_b32_e32 v96, 16, v70
	v_and_b32_e32 v97, 0xffff0000, v70
	s_waitcnt vmcnt(0)
	v_cvt_f32_f16_e32 v89, v75
	v_cvt_f32_f16_sdwa v93, v75 dst_sel:DWORD dst_unused:UNUSED_PAD src0_sel:WORD_1
	v_cvt_f32_f16_e32 v75, v76
	v_cvt_f32_f16_e32 v84, v74
	v_cvt_f32_f16_sdwa v85, v74 dst_sel:DWORD dst_unused:UNUSED_PAD src0_sel:WORD_1
	v_cvt_f32_f16_e32 v91, v77
	v_cvt_f32_f16_sdwa v87, v76 dst_sel:DWORD dst_unused:UNUSED_PAD src0_sel:WORD_1
	v_mul_f32_e32 v76, 0x3fb8aa3b, v75
	v_mul_f32_e32 v75, 0xbfb8aa3b, v75
	v_cvt_f32_f16_sdwa v95, v77 dst_sel:DWORD dst_unused:UNUSED_PAD src0_sel:WORD_1
	v_mul_f32_e32 v77, 0xbfb8aa3b, v84
	v_exp_f32_e32 v86, v75
	v_mul_f32_e32 v75, 0x3fb8aa3b, v85
	v_mul_f32_e32 v85, 0xbfb8aa3b, v85
	v_mul_f32_e32 v88, 0x3fb8aa3b, v89
	v_mul_f32_e32 v89, 0xbfb8aa3b, v89
	v_mul_f32_e32 v74, 0x3fb8aa3b, v84
	v_exp_f32_e32 v84, v77
	v_exp_f32_e32 v85, v85
	v_exp_f32_e32 v92, v89
	v_mul_f32_e32 v89, 0xbfb8aa3b, v91
	v_exp_f32_e32 v94, v89
	v_mul_f32_e32 v89, 0x3fb8aa3b, v93
	v_mul_f32_e32 v93, 0xbfb8aa3b, v93
	v_exp_f32_e32 v93, v93
	v_mul_f32_e32 v77, 0x3fb8aa3b, v87
	v_mul_f32_e32 v87, 0xbfb8aa3b, v87
	v_exp_f32_e32 v87, v87
	v_pk_mul_f32 v[84:85], v[84:85], v[96:97]
	v_mul_f32_e32 v90, 0x3fb8aa3b, v91
	v_mul_f32_e32 v91, 0x3fb8aa3b, v95
	v_mul_f32_e32 v95, 0xbfb8aa3b, v95
	v_cvt_pk_bf16_f32 v70, v84, v85
	v_lshlrev_b32_e32 v84, 16, v71
	v_and_b32_e32 v85, 0xffff0000, v71
	v_exp_f32_e32 v95, v95
	v_pk_mul_f32 v[84:85], v[92:93], v[84:85]
	v_exp_f32_e32 v74, v74
	v_cvt_pk_bf16_f32 v71, v84, v85
	v_lshlrev_b32_e32 v84, 16, v72
	v_and_b32_e32 v85, 0xffff0000, v72
	v_pk_mul_f32 v[84:85], v[86:87], v[84:85]
	v_exp_f32_e32 v75, v75
	v_cvt_pk_bf16_f32 v72, v84, v85
	v_lshlrev_b32_e32 v84, 16, v73
	v_and_b32_e32 v85, 0xffff0000, v73
	v_pk_mul_f32 v[84:85], v[94:95], v[84:85]
	v_exp_f32_e32 v88, v88
	v_cvt_pk_bf16_f32 v73, v84, v85
	v_lshlrev_b32_e32 v85, 2, v83
	v_lshlrev_b32_e32 v84, 9, v83
	v_and_b32_e32 v85, 12, v85
	v_bfe_u32 v83, v83, 2, 2
	v_bitop3_b32 v83, v85, v82, v83 bitop3:0x36
	v_lshl_or_b32 v83, v83, 4, v84
	v_exp_f32_e32 v89, v89
	v_add_u32_e32 v84, s18, v83
	ds_write_b128 v84, v[70:73]
	v_lshlrev_b32_e32 v70, 16, v66
	v_and_b32_e32 v71, 0xffff0000, v66
	v_exp_f32_e32 v76, v76
	v_exp_f32_e32 v77, v77
	v_pk_mul_f32 v[70:71], v[74:75], v[70:71]
	v_exp_f32_e32 v90, v90
	v_cvt_pk_bf16_f32 v66, v70, v71
	v_lshlrev_b32_e32 v70, 16, v67
	v_and_b32_e32 v71, 0xffff0000, v67
	v_exp_f32_e32 v91, v91
	v_pk_mul_f32 v[70:71], v[88:89], v[70:71]
	s_nop 0
	v_cvt_pk_bf16_f32 v67, v70, v71
	v_lshlrev_b32_e32 v70, 16, v68
	v_and_b32_e32 v71, 0xffff0000, v68
	v_pk_mul_f32 v[70:71], v[76:77], v[70:71]
	s_nop 0
	v_cvt_pk_bf16_f32 v68, v70, v71
	v_lshlrev_b32_e32 v70, 16, v69
	v_and_b32_e32 v71, 0xffff0000, v69
	v_pk_mul_f32 v[70:71], v[90:91], v[70:71]
	s_nop 0
	v_cvt_pk_bf16_f32 v69, v70, v71
	v_add_u32_e32 v70, 0, v83
	ds_write_b128 v70, v[66:69]
	v_add_u32_e32 v66, 0xc00, v108
	v_ashrrev_i32_e32 v83, 5, v66
	v_add_u32_e32 v74, s7, v83
	v_ashrrev_i32_e32 v75, 31, v74
	v_lshlrev_b64 v[66:67], 9, v[74:75]
	v_lshlrev_b64 v[74:75], 11, v[74:75]
	v_lshl_add_u64 v[74:75], v[78:79], 0, v[74:75]
	global_load_dwordx4 v[74:77], v[74:75], off nt
	v_lshl_add_u64 v[66:67], s[0:1], 0, v[66:67]
	v_lshl_add_u64 v[70:71], v[66:67], 0, v[80:81]
	v_add_co_u32_e32 v66, vcc, s2, v70
	v_addc_co_u32_e32 v67, vcc, 0, v71, vcc
	global_load_dwordx4 v[66:69], v[66:67], off nt
	v_add_co_u32_e32 v70, vcc, s4, v70
	s_nop 0
	v_addc_co_u32_e32 v71, vcc, 0, v71, vcc
	global_load_dwordx4 v[70:73], v[70:71], off nt
	s_waitcnt vmcnt(2)
	v_cvt_f32_f16_e32 v89, v75
	v_cvt_f32_f16_sdwa v93, v75 dst_sel:DWORD dst_unused:UNUSED_PAD src0_sel:WORD_1
	v_cvt_f32_f16_e32 v75, v76
	v_cvt_f32_f16_e32 v84, v74
	v_cvt_f32_f16_sdwa v85, v74 dst_sel:DWORD dst_unused:UNUSED_PAD src0_sel:WORD_1
	v_cvt_f32_f16_e32 v91, v77
	v_cvt_f32_f16_sdwa v87, v76 dst_sel:DWORD dst_unused:UNUSED_PAD src0_sel:WORD_1
	v_mul_f32_e32 v76, 0x3fb8aa3b, v75
	v_mul_f32_e32 v75, 0xbfb8aa3b, v75
	v_cvt_f32_f16_sdwa v95, v77 dst_sel:DWORD dst_unused:UNUSED_PAD src0_sel:WORD_1
	v_mul_f32_e32 v77, 0xbfb8aa3b, v84
	v_exp_f32_e32 v86, v75
	v_mul_f32_e32 v75, 0x3fb8aa3b, v85
	v_mul_f32_e32 v85, 0xbfb8aa3b, v85
	v_mul_f32_e32 v88, 0x3fb8aa3b, v89
	v_mul_f32_e32 v89, 0xbfb8aa3b, v89
	v_mul_f32_e32 v74, 0x3fb8aa3b, v84
	v_exp_f32_e32 v84, v77
	v_exp_f32_e32 v85, v85
	v_exp_f32_e32 v92, v89
	v_mul_f32_e32 v89, 0xbfb8aa3b, v91
	v_exp_f32_e32 v94, v89
	v_mul_f32_e32 v89, 0x3fb8aa3b, v93
	v_mul_f32_e32 v93, 0xbfb8aa3b, v93
	v_exp_f32_e32 v93, v93
	v_mul_f32_e32 v77, 0x3fb8aa3b, v87
	v_mul_f32_e32 v87, 0xbfb8aa3b, v87
	v_exp_f32_e32 v87, v87
	v_mul_f32_e32 v90, 0x3fb8aa3b, v91
	v_mul_f32_e32 v91, 0x3fb8aa3b, v95
	v_mul_f32_e32 v95, 0xbfb8aa3b, v95
	v_exp_f32_e32 v95, v95
	v_exp_f32_e32 v74, v74
	v_exp_f32_e32 v75, v75
	v_exp_f32_e32 v88, v88
	v_exp_f32_e32 v89, v89
	v_exp_f32_e32 v76, v76
	v_exp_f32_e32 v77, v77
	v_exp_f32_e32 v90, v90
	v_exp_f32_e32 v91, v91
	s_waitcnt vmcnt(1)
	v_lshlrev_b32_e32 v96, 16, v66
	v_and_b32_e32 v97, 0xffff0000, v66
	v_pk_mul_f32 v[84:85], v[84:85], v[96:97]
	s_nop 0
	v_cvt_pk_bf16_f32 v66, v84, v85
	v_lshlrev_b32_e32 v84, 16, v67
	v_and_b32_e32 v85, 0xffff0000, v67
	v_pk_mul_f32 v[84:85], v[92:93], v[84:85]
	s_nop 0
	v_cvt_pk_bf16_f32 v67, v84, v85
	v_lshlrev_b32_e32 v84, 16, v68
	v_and_b32_e32 v85, 0xffff0000, v68
	v_pk_mul_f32 v[84:85], v[86:87], v[84:85]
	s_nop 0
	v_cvt_pk_bf16_f32 v68, v84, v85
	v_lshlrev_b32_e32 v84, 16, v69
	v_and_b32_e32 v85, 0xffff0000, v69
	v_pk_mul_f32 v[84:85], v[94:95], v[84:85]
	s_nop 0
	v_cvt_pk_bf16_f32 v69, v84, v85
	v_lshlrev_b32_e32 v85, 2, v83
	v_lshlrev_b32_e32 v84, 9, v83
	v_and_b32_e32 v85, 12, v85
	v_bfe_u32 v83, v83, 2, 2
	v_bitop3_b32 v83, v85, v82, v83 bitop3:0x36
	v_lshl_or_b32 v83, v83, 4, v84
	v_add_u32_e32 v84, s18, v83
	ds_write_b128 v84, v[66:69]
	s_waitcnt vmcnt(0)
	v_lshlrev_b32_e32 v66, 16, v70
	v_and_b32_e32 v67, 0xffff0000, v70
	v_lshlrev_b32_e32 v68, 16, v71
	v_and_b32_e32 v69, 0xffff0000, v71
	v_pk_mul_f32 v[66:67], v[74:75], v[66:67]
	v_pk_mul_f32 v[68:69], v[88:89], v[68:69]
	v_cvt_pk_bf16_f32 v66, v66, v67
	v_cvt_pk_bf16_f32 v67, v68, v69
	v_lshlrev_b32_e32 v68, 16, v72
	v_and_b32_e32 v69, 0xffff0000, v72
	v_lshlrev_b32_e32 v70, 16, v73
	v_and_b32_e32 v71, 0xffff0000, v73
	v_pk_mul_f32 v[68:69], v[76:77], v[68:69]
	v_pk_mul_f32 v[70:71], v[90:91], v[70:71]
	v_cvt_pk_bf16_f32 v68, v68, v69
	v_cvt_pk_bf16_f32 v69, v70, v71
	v_add_u32_e32 v70, 0, v83
	ds_write_b128 v70, v[66:69]
	v_add_u32_e32 v66, 0xe00, v108
	v_ashrrev_i32_e32 v83, 5, v66
	v_add_u32_e32 v74, s7, v83
	v_ashrrev_i32_e32 v75, 31, v74
	v_lshlrev_b64 v[66:67], 9, v[74:75]
	v_lshl_add_u64 v[66:67], s[0:1], 0, v[66:67]
	v_lshl_add_u64 v[66:67], v[66:67], 0, v[80:81]
	v_add_co_u32_e32 v68, vcc, s2, v66
	v_lshlrev_b64 v[74:75], 11, v[74:75]
	s_nop 0
	v_addc_co_u32_e32 v69, vcc, 0, v67, vcc
	v_add_co_u32_e32 v66, vcc, s4, v66
	v_lshl_add_u64 v[74:75], v[78:79], 0, v[74:75]
	s_nop 0
	v_addc_co_u32_e32 v67, vcc, 0, v67, vcc
	global_load_dwordx4 v[70:73], v[68:69], off nt
	global_load_dwordx4 v[66:69], v[66:67], off nt
	global_load_dwordx4 v[74:77], v[74:75], off nt
	s_waitcnt vmcnt(2)
	v_lshlrev_b32_e32 v92, 16, v70
	v_and_b32_e32 v93, 0xffff0000, v70
	s_waitcnt vmcnt(0)
	v_cvt_f32_f16_e32 v85, v75
	v_cvt_f32_f16_sdwa v89, v75 dst_sel:DWORD dst_unused:UNUSED_PAD src0_sel:WORD_1
	v_cvt_f32_f16_e32 v75, v76
	v_cvt_f32_f16_e32 v78, v74
	v_cvt_f32_f16_sdwa v79, v74 dst_sel:DWORD dst_unused:UNUSED_PAD src0_sel:WORD_1
	v_cvt_f32_f16_e32 v87, v77
	v_cvt_f32_f16_sdwa v81, v76 dst_sel:DWORD dst_unused:UNUSED_PAD src0_sel:WORD_1
	v_mul_f32_e32 v76, 0x3fb8aa3b, v75
	v_mul_f32_e32 v75, 0xbfb8aa3b, v75
	v_cvt_f32_f16_sdwa v91, v77 dst_sel:DWORD dst_unused:UNUSED_PAD src0_sel:WORD_1
	v_mul_f32_e32 v77, 0xbfb8aa3b, v78
	v_exp_f32_e32 v80, v75
	v_mul_f32_e32 v75, 0x3fb8aa3b, v79
	v_mul_f32_e32 v79, 0xbfb8aa3b, v79
	v_mul_f32_e32 v84, 0x3fb8aa3b, v85
	v_mul_f32_e32 v85, 0xbfb8aa3b, v85
	v_mul_f32_e32 v74, 0x3fb8aa3b, v78
	v_exp_f32_e32 v78, v77
	v_exp_f32_e32 v79, v79
	v_exp_f32_e32 v88, v85
	v_mul_f32_e32 v85, 0xbfb8aa3b, v87
	v_exp_f32_e32 v90, v85
	v_mul_f32_e32 v85, 0x3fb8aa3b, v89
	v_mul_f32_e32 v89, 0xbfb8aa3b, v89
	v_exp_f32_e32 v89, v89
	v_mul_f32_e32 v77, 0x3fb8aa3b, v81
	v_mul_f32_e32 v81, 0xbfb8aa3b, v81
	v_exp_f32_e32 v81, v81
	v_pk_mul_f32 v[78:79], v[78:79], v[92:93]
	v_mul_f32_e32 v86, 0x3fb8aa3b, v87
	v_mul_f32_e32 v87, 0x3fb8aa3b, v91
	v_mul_f32_e32 v91, 0xbfb8aa3b, v91
	v_cvt_pk_bf16_f32 v70, v78, v79
	v_lshlrev_b32_e32 v78, 16, v71
	v_and_b32_e32 v79, 0xffff0000, v71
	v_exp_f32_e32 v91, v91
	v_pk_mul_f32 v[78:79], v[88:89], v[78:79]
	v_exp_f32_e32 v74, v74
	v_cvt_pk_bf16_f32 v71, v78, v79
	v_lshlrev_b32_e32 v78, 16, v72
	v_and_b32_e32 v79, 0xffff0000, v72
	v_pk_mul_f32 v[78:79], v[80:81], v[78:79]
	v_bfe_u32 v80, v83, 2, 2
	v_cvt_pk_bf16_f32 v72, v78, v79
	v_lshlrev_b32_e32 v78, 16, v73
	v_and_b32_e32 v79, 0xffff0000, v73
	v_pk_mul_f32 v[78:79], v[90:91], v[78:79]
	v_exp_f32_e32 v75, v75
	v_cvt_pk_bf16_f32 v73, v78, v79
	v_lshlrev_b32_e32 v79, 2, v83
	v_and_b32_e32 v79, 12, v79
	v_lshlrev_b32_e32 v78, 9, v83
	v_bitop3_b32 v79, v79, v82, v80 bitop3:0x36
	v_lshl_or_b32 v78, v79, 4, v78
	v_exp_f32_e32 v84, v84
	v_exp_f32_e32 v85, v85
	v_add_u32_e32 v79, s18, v78
	ds_write_b128 v79, v[70:73]
	v_lshlrev_b32_e32 v70, 16, v66
	v_and_b32_e32 v71, 0xffff0000, v66
	v_exp_f32_e32 v76, v76
	v_exp_f32_e32 v77, v77
	v_pk_mul_f32 v[70:71], v[74:75], v[70:71]
	v_exp_f32_e32 v86, v86
	v_cvt_pk_bf16_f32 v66, v70, v71
	v_lshlrev_b32_e32 v70, 16, v67
	v_and_b32_e32 v71, 0xffff0000, v67
	v_exp_f32_e32 v87, v87
	v_pk_mul_f32 v[70:71], v[84:85], v[70:71]
	s_nop 0
	v_cvt_pk_bf16_f32 v67, v70, v71
	v_lshlrev_b32_e32 v70, 16, v68
	v_and_b32_e32 v71, 0xffff0000, v68
	v_pk_mul_f32 v[70:71], v[76:77], v[70:71]
	s_nop 0
	v_cvt_pk_bf16_f32 v68, v70, v71
	v_lshlrev_b32_e32 v70, 16, v69
	v_and_b32_e32 v71, 0xffff0000, v69
	v_pk_mul_f32 v[70:71], v[86:87], v[70:71]
	s_nop 0
	v_cvt_pk_bf16_f32 v69, v70, v71
	v_add_u32_e32 v70, 0, v78
	ds_write_b128 v70, v[66:69]
	v_lshlrev_b32_e32 v67, 2, v146
	v_bfe_u32 v66, v146, 2, 2
	v_and_b32_e32 v67, 12, v67
	v_lshl_add_u32 v68, v111, 9, 0
	v_bitop3_b32 v69, v67, v147, v66 bitop3:0x36
	v_lshl_add_u32 v69, v69, 4, v68
	s_waitcnt lgkmcnt(0)
	s_barrier
	ds_read_b128 v[90:93], v69
	v_bitop3_b32 v69, v67, v113, v66 bitop3:0x36
	v_lshl_add_u32 v69, v69, 4, v68
	ds_read_b128 v[94:97], v69
	v_bitop3_b32 v69, v67, v114, v66 bitop3:0x36
	v_lshl_add_u32 v69, v69, 4, v68
	ds_read_b128 v[86:89], v69
	v_bitop3_b32 v69, v67, v115, v66 bitop3:0x36
	v_lshl_add_u32 v69, v69, 4, v68
	ds_read_b128 v[82:85], v69
	v_bitop3_b32 v69, v67, v116, v66 bitop3:0x36
	v_lshl_add_u32 v69, v69, 4, v68
	ds_read_b128 v[78:81], v69
	v_bitop3_b32 v69, v67, v118, v66 bitop3:0x36
	v_lshl_add_u32 v69, v69, 4, v68
	v_or_b32_e32 v110, v67, v66
	ds_read_b128 v[74:77], v69
	v_bitop3_b32 v69, v67, v119, v66 bitop3:0x36
	v_bitop3_b32 v66, v67, v123, v66 bitop3:0x36
	v_lshl_add_u32 v69, v69, 4, v68
	v_lshl_add_u32 v66, v66, 4, v68
	ds_read_b128 v[70:73], v69
	ds_read_b128 v[66:69], v66
	v_xor_b32_e32 v127, v110, v147
	v_xor_b32_e32 v125, v113, v110
	v_xor_b32_e32 v124, v114, v110
	v_xor_b32_e32 v122, v115, v110
	v_xor_b32_e32 v121, v116, v110
	v_xor_b32_e32 v120, v118, v110
	v_xor_b32_e32 v119, v119, v110
	v_xor_b32_e32 v118, v123, v110
	v_lshl_add_u32 v140, v127, 4, v117
	v_lshl_add_u32 v139, v125, 4, v117
	v_lshl_add_u32 v138, v124, 4, v117
	v_lshl_add_u32 v137, v122, 4, v117
	v_lshl_add_u32 v136, v121, 4, v117
	v_lshl_add_u32 v134, v120, 4, v117
	v_lshl_add_u32 v133, v119, 4, v117
	v_lshl_add_u32 v131, v118, 4, v117
	v_mov_b32_e32 v113, 0
	v_mov_b32_e32 v114, 0
	v_mov_b32_e32 v115, 0
	v_mov_b32_e32 v116, 0
	s_cbranch_scc1 .LBB0_484
	ds_read_b128 v[142:145], v140
	ds_read_b128 v[150:153], v139
	v_cmp_gt_i32_e32 vcc, v148, v111
	v_mov_b32_e32 v114, s19
	v_or_b32_e32 v115, 2, v148
	v_or_b32_e32 v116, 3, v148
	s_waitcnt lgkmcnt(1)
	v_mfma_f32_16x16x32_bf16 v[142:145], v[142:145], v[90:93], 0
	s_waitcnt lgkmcnt(0)
	v_mfma_f32_16x16x32_bf16 v[142:145], v[150:153], v[94:97], v[142:145]
	ds_read_b128 v[150:153], v138
	s_waitcnt lgkmcnt(0)
	v_mfma_f32_16x16x32_bf16 v[142:145], v[150:153], v[86:89], v[142:145]
	ds_read_b128 v[150:153], v137
	s_waitcnt lgkmcnt(0)
	v_mfma_f32_16x16x32_bf16 v[142:145], v[150:153], v[82:85], v[142:145]
	ds_read_b128 v[150:153], v136
	s_waitcnt lgkmcnt(0)
	v_mfma_f32_16x16x32_bf16 v[142:145], v[150:153], v[78:81], v[142:145]
	ds_read_b128 v[150:153], v134
	s_waitcnt lgkmcnt(0)
	v_mfma_f32_16x16x32_bf16 v[142:145], v[150:153], v[74:77], v[142:145]
	ds_read_b128 v[150:153], v133
	s_waitcnt lgkmcnt(0)
	v_mfma_f32_16x16x32_bf16 v[142:145], v[150:153], v[70:73], v[142:145]
	ds_read_b128 v[150:153], v131
	s_waitcnt lgkmcnt(0)
	v_mfma_f32_16x16x32_bf16 v[142:145], v[150:153], v[66:69], v[142:145]
	s_nop 7
	v_cndmask_b32_e32 v113, v142, v114, vcc
	v_cmp_lt_i32_e32 vcc, v148, v111
	s_nop 1
	v_cndmask_b32_e32 v113, v113, v142, vcc
	v_cndmask_b32_e32 v114, 0, v143, vcc
	v_cmp_le_i32_e32 vcc, v115, v111
	s_nop 1
	v_cndmask_b32_e32 v115, 0, v144, vcc
	v_cmp_le_i32_e32 vcc, v116, v111
	s_nop 1
	v_cndmask_b32_e32 v116, 0, v145, vcc
